# phase-0 hyena filter MLP weight loads batched/pipelined (same fma order), on top of GEMM ring loops, conv d-loop, hyena post/pre fast paths
# speedup vs baseline: 1.1367x; 1.0754x over previous
; DI void hyena_filter_pos(const Params& p, int t, int w, int lane, float* sz, float* sh0, float* sh1) {
;     ...
;   const float fr = p.f_freq[lane];
;   float a = p.f_b1[lane];
; #pragma unroll 1
;   for (int i = 0; i < 33; ++i) a += sz[w * 40 + i] * p.f_w1[i * 64 + lane];
;   sh0[w * 64 + lane] = sinf(fr * a);
.LBB0_29:
	s_or_b64 exec, exec, s[42:43]
	s_waitcnt lgkmcnt(0)
	s_barrier
	global_load_dword v6, v[26:27], off
	global_load_dword v7, v[28:29], off
	s_mov_b32 s68, 0x1000
	s_mov_b32 s69, 0
	v_lshl_add_u64 v[234:235], v[34:35], 0, s[68:69]
	v_lshl_add_u64 v[236:237], v[234:235], 0, s[68:69]
	global_load_dword v167, v[34:35], off
	global_load_dword v168, v[34:35], off offset:256
	global_load_dword v169, v[34:35], off offset:512
	global_load_dword v170, v[34:35], off offset:768
	global_load_dword v171, v[34:35], off offset:1024
	global_load_dword v172, v[34:35], off offset:1280
	global_load_dword v173, v[34:35], off offset:1536
	global_load_dword v174, v[34:35], off offset:1792
	global_load_dword v175, v[34:35], off offset:2048
	global_load_dword v176, v[34:35], off offset:2304
	global_load_dword v177, v[34:35], off offset:2560
	global_load_dword v178, v[34:35], off offset:2816
	global_load_dword v179, v[34:35], off offset:3072
	global_load_dword v180, v[34:35], off offset:3328
	global_load_dword v181, v[34:35], off offset:3584
	global_load_dword v182, v[34:35], off offset:3840
	global_load_dword v183, v[234:235], off
	global_load_dword v184, v[234:235], off offset:256
	global_load_dword v185, v[234:235], off offset:512
	global_load_dword v186, v[234:235], off offset:768
	global_load_dword v187, v[234:235], off offset:1024
	global_load_dword v188, v[234:235], off offset:1280
	global_load_dword v189, v[234:235], off offset:1536
	global_load_dword v190, v[234:235], off offset:1792
	global_load_dword v191, v[234:235], off offset:2048
	global_load_dword v192, v[234:235], off offset:2304
	global_load_dword v193, v[234:235], off offset:2560
	global_load_dword v194, v[234:235], off offset:2816
	global_load_dword v195, v[234:235], off offset:3072
	global_load_dword v197, v[234:235], off offset:3328
	global_load_dword v198, v[234:235], off offset:3584
	global_load_dword v199, v[234:235], off offset:3840
	global_load_dword v200, v[236:237], off
	ds_read_b128 v[80:83], v49
	ds_read_b128 v[84:87], v49 offset:16
	ds_read_b128 v[88:91], v49 offset:32
	ds_read_b128 v[92:95], v49 offset:48
	ds_read_b128 v[96:99], v49 offset:64
	ds_read_b128 v[100:103], v49 offset:80
	ds_read_b128 v[104:107], v49 offset:96
	ds_read_b128 v[108:111], v49 offset:112
	ds_read_b32 v112, v49 offset:128
	s_waitcnt lgkmcnt(0)
	s_waitcnt vmcnt(32)
	v_fmac_f32_e32 v7, v80, v167
	s_waitcnt vmcnt(31)
	v_fmac_f32_e32 v7, v81, v168
	s_waitcnt vmcnt(30)
	v_fmac_f32_e32 v7, v82, v169
	s_waitcnt vmcnt(29)
	v_fmac_f32_e32 v7, v83, v170
	s_waitcnt vmcnt(28)
	v_fmac_f32_e32 v7, v84, v171
	s_waitcnt vmcnt(27)
	v_fmac_f32_e32 v7, v85, v172
	s_waitcnt vmcnt(26)
	v_fmac_f32_e32 v7, v86, v173
	s_waitcnt vmcnt(25)
	v_fmac_f32_e32 v7, v87, v174
	s_waitcnt vmcnt(24)
	v_fmac_f32_e32 v7, v88, v175
	s_waitcnt vmcnt(23)
	v_fmac_f32_e32 v7, v89, v176
	s_waitcnt vmcnt(22)
	v_fmac_f32_e32 v7, v90, v177
	s_waitcnt vmcnt(21)
	v_fmac_f32_e32 v7, v91, v178
	s_waitcnt vmcnt(20)
	v_fmac_f32_e32 v7, v92, v179
	s_waitcnt vmcnt(19)
	v_fmac_f32_e32 v7, v93, v180
	s_waitcnt vmcnt(18)
	v_fmac_f32_e32 v7, v94, v181
	s_waitcnt vmcnt(17)
	v_fmac_f32_e32 v7, v95, v182
	s_waitcnt vmcnt(16)
	v_fmac_f32_e32 v7, v96, v183
	s_waitcnt vmcnt(15)
	v_fmac_f32_e32 v7, v97, v184
	s_waitcnt vmcnt(14)
	v_fmac_f32_e32 v7, v98, v185
	s_waitcnt vmcnt(13)
	v_fmac_f32_e32 v7, v99, v186
	s_waitcnt vmcnt(12)
	v_fmac_f32_e32 v7, v100, v187
	s_waitcnt vmcnt(11)
	v_fmac_f32_e32 v7, v101, v188
	s_waitcnt vmcnt(10)
	v_fmac_f32_e32 v7, v102, v189
	s_waitcnt vmcnt(9)
	v_fmac_f32_e32 v7, v103, v190
	s_waitcnt vmcnt(8)
	v_fmac_f32_e32 v7, v104, v191
	s_waitcnt vmcnt(7)
	v_fmac_f32_e32 v7, v105, v192
	s_waitcnt vmcnt(6)
	v_fmac_f32_e32 v7, v106, v193
	s_waitcnt vmcnt(5)
	v_fmac_f32_e32 v7, v107, v194
	s_waitcnt vmcnt(4)
	v_fmac_f32_e32 v7, v108, v195
	s_waitcnt vmcnt(3)
	v_fmac_f32_e32 v7, v109, v197
	s_waitcnt vmcnt(2)
	v_fmac_f32_e32 v7, v110, v198
	s_waitcnt vmcnt(1)
	v_fmac_f32_e32 v7, v111, v199
	s_waitcnt vmcnt(0)
	v_fmac_f32_e32 v7, v112, v200
	v_mul_f32_e32 v2, v6, v7
	v_and_b32_e32 v3, 0x7fffffff, v2
	v_cmp_nlt_f32_e64 s[6:7], |v2|, s54
	s_and_saveexec_b64 s[8:9], s[6:7]
	s_xor_b64 s[14:15], exec, s[8:9]
	s_cbranch_execz .LBB0_33
	v_lshrrev_b32_e32 v7, 23, v3
	v_add_u32_e32 v7, 0xffffff88, v7
	v_cmp_lt_u32_e32 vcc, 63, v7
	s_nop 1
	v_cndmask_b32_e32 v8, 0, v68, vcc
	v_add_u32_e32 v7, v8, v7
	v_cmp_lt_u32_e64 s[6:7], 31, v7
	s_nop 1
	v_cndmask_b32_e64 v8, 0, v69, s[6:7]
	v_add_u32_e32 v7, v8, v7
	v_cmp_lt_u32_e64 s[8:9], 31, v7
	s_nop 1
	v_cndmask_b32_e64 v8, 0, v69, s[8:9]
	v_add_u32_e32 v7, v8, v7
	v_and_b32_e32 v8, 0x7fffff, v3
	v_or_b32_e32 v44, 0x800000, v8
	v_mad_u64_u32 v[8:9], s[12:13], v44, s55, 0
	v_mov_b32_e32 v18, v9
	v_mad_u64_u32 v[10:11], s[12:13], v44, s56, v[18:19]
	v_mov_b32_e32 v18, v11
	v_mad_u64_u32 v[12:13], s[12:13], v44, s57, v[18:19]
	v_mov_b32_e32 v18, v13
	v_mad_u64_u32 v[14:15], s[12:13], v44, s58, v[18:19]
	v_mov_b32_e32 v18, v15
	v_mad_u64_u32 v[16:17], s[12:13], v44, s59, v[18:19]
	v_mov_b32_e32 v18, v17
	v_mad_u64_u32 v[42:43], s[12:13], v44, s60, v[18:19]
	v_mov_b32_e32 v18, v43
	v_mad_u64_u32 v[76:77], s[12:13], v44, s61, v[18:19]
	v_cndmask_b32_e32 v9, v42, v14, vcc
	v_cndmask_b32_e32 v11, v76, v16, vcc
	v_cndmask_b32_e32 v15, v77, v42, vcc
	v_cndmask_b32_e64 v13, v11, v9, s[6:7]
	v_cndmask_b32_e64 v11, v15, v11, s[6:7]
	v_cndmask_b32_e32 v15, v16, v12, vcc
	v_cndmask_b32_e64 v9, v9, v15, s[6:7]
	v_cndmask_b32_e64 v11, v11, v13, s[8:9]
	v_cndmask_b32_e64 v13, v13, v9, s[8:9]
	v_sub_u32_e32 v16, 32, v7
	v_alignbit_b32 v17, v11, v13, v16
	v_cmp_eq_u32_e64 s[12:13], 0, v7
	v_cndmask_b32_e32 v10, v14, v10, vcc
; DI void hyena_filter_pos(const Params& p, int t, int w, int lane, float* sz, float* sh0, float* sh1) {
;     ...
;   sh0[w * 64 + lane] = sinf(fr * a);
;   __syncthreads();
;   a = p.f_b2[lane];
; #pragma unroll 4
;   for (int i = 0; i < 64; ++i) a += sh0[w * 64 + i] * p.f_w2[i * 64 + lane];
;   sh1[w * 64 + lane] = sinf(fr * a);
	v_cndmask_b32_e32 v8, v12, v8, vcc
	v_cndmask_b32_e64 v7, v17, v11, s[12:13]
	v_cndmask_b32_e64 v11, v15, v10, s[6:7]
	v_cndmask_b32_e64 v9, v9, v11, s[8:9]
	v_alignbit_b32 v14, v13, v9, v16
	v_cndmask_b32_e64 v13, v14, v13, s[12:13]
	v_bfe_u32 v17, v7, 29, 1
	v_cndmask_b32_e64 v8, v10, v8, s[6:7]
	v_alignbit_b32 v14, v7, v13, 30
	v_sub_u32_e32 v18, 0, v17
	v_cndmask_b32_e64 v8, v11, v8, s[8:9]
	v_xor_b32_e32 v14, v14, v18
	v_alignbit_b32 v10, v9, v8, v16
	v_cndmask_b32_e64 v9, v10, v9, s[12:13]
	v_ffbh_u32_e32 v11, v14
	v_alignbit_b32 v10, v13, v9, 30
	v_min_u32_e32 v11, 32, v11
	v_alignbit_b32 v8, v9, v8, 30
	v_xor_b32_e32 v10, v10, v18
	v_sub_u32_e32 v12, 31, v11
	v_xor_b32_e32 v8, v8, v18
	v_alignbit_b32 v13, v14, v10, v12
	v_alignbit_b32 v8, v10, v8, v12
	v_alignbit_b32 v9, v13, v8, 9
	v_ffbh_u32_e32 v10, v9
	v_min_u32_e32 v10, 32, v10
	v_lshrrev_b32_e32 v15, 29, v7
	v_not_b32_e32 v12, v10
	v_alignbit_b32 v8, v9, v8, v12
	v_lshlrev_b32_e32 v9, 31, v15
	v_or_b32_e32 v12, 0x33000000, v9
	v_add_lshl_u32 v10, v10, v11, 23
	v_lshrrev_b32_e32 v8, 9, v8
	v_sub_u32_e32 v10, v12, v10
	v_or_b32_e32 v9, 0.5, v9
	v_lshlrev_b32_e32 v11, 23, v11
	v_or_b32_e32 v8, v10, v8
	v_lshrrev_b32_e32 v10, 9, v13
	v_sub_u32_e32 v9, v9, v11
	v_or_b32_e32 v9, v10, v9
	v_mul_f32_e32 v10, 0x3fc90fda, v9
	v_fma_f32 v11, v9, s62, -v10
	v_fmac_f32_e32 v11, 0x33a22168, v9
	v_fmac_f32_e32 v11, 0x3fc90fda, v8
	v_lshrrev_b32_e32 v7, 30, v7
	v_add_f32_e32 v8, v10, v11
	v_add_u32_e32 v7, v17, v7
.LBB0_33:
	s_andn2_saveexec_b64 s[6:7], s[14:15]
	v_mul_f32_e64 v7, |v2|, s63
	v_rndne_f32_e32 v9, v7
	v_cvt_i32_f32_e32 v7, v9
	v_fma_f32 v8, v9, s64, |v2|
	v_fmac_f32_e32 v8, 0xb3a22168, v9
	v_fmac_f32_e32 v8, 0xa7c234c4, v9
	s_or_b64 exec, exec, s[6:7]
	v_mul_f32_e32 v9, v8, v8
	v_fmamk_f32 v10, v9, 0xb94c1982, v65
	v_fmaak_f32 v10, v9, v10, 0xbe2aaa9d
	v_mul_f32_e32 v10, v9, v10
	v_fmac_f32_e32 v8, v8, v10
	v_fmamk_f32 v10, v9, 0x37d75334, v66
	v_fmaak_f32 v10, v9, v10, 0x3d2aabf7
	v_fmaak_f32 v10, v9, v10, 0xbf000004
	v_fma_f32 v9, v9, v10, 1.0
	v_and_b32_e32 v10, 1, v7
	v_lshlrev_b32_e32 v7, 30, v7
	v_cmp_eq_u32_e32 vcc, 0, v10
	v_and_b32_e32 v7, 0x80000000, v7
	v_xor_b32_e32 v3, v3, v2
	v_cndmask_b32_e32 v8, v9, v8, vcc
	v_xor_b32_e32 v3, v3, v7
	v_xor_b32_e32 v3, v3, v8
	v_cmp_class_f32_e64 vcc, v2, s67
	s_mov_b32 s6, 0
	s_nop 0
	v_cndmask_b32_e32 v2, v71, v3, vcc
	ds_write_b32 v51, v2 offset:640
	s_waitcnt lgkmcnt(0)
	s_barrier
	global_load_dword v7, v[30:31], off
	s_mov_b32 s68, 0x1000
	s_mov_b32 s69, 0
	v_lshl_add_u64 v[234:235], v[36:37], 0, s[68:69]
	v_lshl_add_u64 v[236:237], v[234:235], 0, s[68:69]
	v_lshl_add_u64 v[238:239], v[236:237], 0, s[68:69]
	global_load_dword v167, v[36:37], off offset:-512
	global_load_dword v168, v[36:37], off offset:-256
	global_load_dword v169, v[36:37], off
	global_load_dword v170, v[36:37], off offset:256
	global_load_dword v171, v[36:37], off offset:512
	global_load_dword v172, v[36:37], off offset:768
	global_load_dword v173, v[36:37], off offset:1024
	global_load_dword v174, v[36:37], off offset:1280
	global_load_dword v175, v[36:37], off offset:1536
	global_load_dword v176, v[36:37], off offset:1792
	global_load_dword v177, v[36:37], off offset:2048
	global_load_dword v178, v[36:37], off offset:2304
	global_load_dword v179, v[36:37], off offset:2560
	global_load_dword v180, v[36:37], off offset:2816
	global_load_dword v181, v[36:37], off offset:3072
	global_load_dword v182, v[36:37], off offset:3328
	global_load_dword v183, v[234:235], off offset:-512
	global_load_dword v184, v[234:235], off offset:-256
	global_load_dword v185, v[234:235], off
	global_load_dword v186, v[234:235], off offset:256
	global_load_dword v187, v[234:235], off offset:512
	global_load_dword v188, v[234:235], off offset:768
	global_load_dword v189, v[234:235], off offset:1024
	global_load_dword v190, v[234:235], off offset:1280
	global_load_dword v191, v[234:235], off offset:1536
	global_load_dword v192, v[234:235], off offset:1792
	global_load_dword v193, v[234:235], off offset:2048
	global_load_dword v194, v[234:235], off offset:2304
	global_load_dword v195, v[234:235], off offset:2560
	global_load_dword v197, v[234:235], off offset:2816
	global_load_dword v198, v[234:235], off offset:3072
	global_load_dword v199, v[234:235], off offset:3328
	global_load_dword v200, v[236:237], off offset:-512
	global_load_dword v201, v[236:237], off offset:-256
	global_load_dword v202, v[236:237], off
	global_load_dword v203, v[236:237], off offset:256
	global_load_dword v204, v[236:237], off offset:512
	global_load_dword v205, v[236:237], off offset:768
	global_load_dword v206, v[236:237], off offset:1024
	global_load_dword v207, v[236:237], off offset:1280
	global_load_dword v208, v[236:237], off offset:1536
	global_load_dword v209, v[236:237], off offset:1792
	global_load_dword v210, v[236:237], off offset:2048
	global_load_dword v211, v[236:237], off offset:2304
	global_load_dword v212, v[236:237], off offset:2560
	global_load_dword v213, v[236:237], off offset:2816
	global_load_dword v214, v[236:237], off offset:3072
	global_load_dword v215, v[236:237], off offset:3328
	global_load_dword v216, v[238:239], off offset:-512
	global_load_dword v217, v[238:239], off offset:-256
	global_load_dword v218, v[238:239], off
	global_load_dword v219, v[238:239], off offset:256
	global_load_dword v220, v[238:239], off offset:512
	global_load_dword v221, v[238:239], off offset:768
	global_load_dword v222, v[238:239], off offset:1024
	global_load_dword v223, v[238:239], off offset:1280
	global_load_dword v224, v[238:239], off offset:1536
	global_load_dword v225, v[238:239], off offset:1792
	global_load_dword v226, v[238:239], off offset:2048
	global_load_dword v227, v[238:239], off offset:2304
	global_load_dword v228, v[238:239], off offset:2560
	global_load_dword v229, v[238:239], off offset:2816
	global_load_dword v230, v[238:239], off offset:3072
	global_load_dword v231, v[238:239], off offset:3328
	ds_read_b128 v[80:83], v54
	ds_read_b128 v[84:87], v54 offset:16
	ds_read_b128 v[88:91], v54 offset:32
	ds_read_b128 v[92:95], v54 offset:48
	ds_read_b128 v[96:99], v54 offset:64
	ds_read_b128 v[100:103], v54 offset:80
	ds_read_b128 v[104:107], v54 offset:96
	ds_read_b128 v[108:111], v54 offset:112
	ds_read_b128 v[112:115], v54 offset:128
	ds_read_b128 v[116:119], v54 offset:144
	ds_read_b128 v[120:123], v54 offset:160
	ds_read_b128 v[124:127], v54 offset:176
	ds_read_b128 v[128:131], v54 offset:192
	ds_read_b128 v[132:135], v54 offset:208
	ds_read_b128 v[136:139], v54 offset:224
	ds_read_b128 v[140:143], v54 offset:240
	s_waitcnt lgkmcnt(0)
; DI void hyena_filter_pos(const Params& p, int t, int w, int lane, float* sz, float* sh0, float* sh1) {
;     ...
; #pragma unroll 4
;   for (int i = 0; i < 64; ++i) a += sh0[w * 64 + i] * p.f_w2[i * 64 + lane];
;   sh1[w * 64 + lane] = sinf(fr * a);
	s_waitcnt vmcnt(63)
	v_fmac_f32_e32 v7, v80, v167
	s_waitcnt vmcnt(62)
	v_fmac_f32_e32 v7, v81, v168
	s_waitcnt vmcnt(61)
	v_fmac_f32_e32 v7, v82, v169
	s_waitcnt vmcnt(60)
	v_fmac_f32_e32 v7, v83, v170
	s_waitcnt vmcnt(59)
	v_fmac_f32_e32 v7, v84, v171
	s_waitcnt vmcnt(58)
	v_fmac_f32_e32 v7, v85, v172
	s_waitcnt vmcnt(57)
	v_fmac_f32_e32 v7, v86, v173
	s_waitcnt vmcnt(56)
	v_fmac_f32_e32 v7, v87, v174
	s_waitcnt vmcnt(55)
	v_fmac_f32_e32 v7, v88, v175
	s_waitcnt vmcnt(54)
	v_fmac_f32_e32 v7, v89, v176
	s_waitcnt vmcnt(53)
	v_fmac_f32_e32 v7, v90, v177
	s_waitcnt vmcnt(52)
	v_fmac_f32_e32 v7, v91, v178
	s_waitcnt vmcnt(51)
	v_fmac_f32_e32 v7, v92, v179
	s_waitcnt vmcnt(50)
	v_fmac_f32_e32 v7, v93, v180
	s_waitcnt vmcnt(49)
	v_fmac_f32_e32 v7, v94, v181
	s_waitcnt vmcnt(48)
	v_fmac_f32_e32 v7, v95, v182
	s_waitcnt vmcnt(47)
	v_fmac_f32_e32 v7, v96, v183
	s_waitcnt vmcnt(46)
	v_fmac_f32_e32 v7, v97, v184
	s_waitcnt vmcnt(45)
	v_fmac_f32_e32 v7, v98, v185
	s_waitcnt vmcnt(44)
	v_fmac_f32_e32 v7, v99, v186
	s_waitcnt vmcnt(43)
	v_fmac_f32_e32 v7, v100, v187
	s_waitcnt vmcnt(42)
	v_fmac_f32_e32 v7, v101, v188
	s_waitcnt vmcnt(41)
	v_fmac_f32_e32 v7, v102, v189
	s_waitcnt vmcnt(40)
	v_fmac_f32_e32 v7, v103, v190
	s_waitcnt vmcnt(39)
	v_fmac_f32_e32 v7, v104, v191
	s_waitcnt vmcnt(38)
	v_fmac_f32_e32 v7, v105, v192
	s_waitcnt vmcnt(37)
	v_fmac_f32_e32 v7, v106, v193
	s_waitcnt vmcnt(36)
	v_fmac_f32_e32 v7, v107, v194
	s_waitcnt vmcnt(35)
	v_fmac_f32_e32 v7, v108, v195
	s_waitcnt vmcnt(34)
	v_fmac_f32_e32 v7, v109, v197
	s_waitcnt vmcnt(33)
	v_fmac_f32_e32 v7, v110, v198
	s_waitcnt vmcnt(32)
	v_fmac_f32_e32 v7, v111, v199
	s_waitcnt vmcnt(31)
	v_fmac_f32_e32 v7, v112, v200
	s_waitcnt vmcnt(30)
	v_fmac_f32_e32 v7, v113, v201
	s_waitcnt vmcnt(29)
	v_fmac_f32_e32 v7, v114, v202
	s_waitcnt vmcnt(28)
	v_fmac_f32_e32 v7, v115, v203
	s_waitcnt vmcnt(27)
	v_fmac_f32_e32 v7, v116, v204
	s_waitcnt vmcnt(26)
	v_fmac_f32_e32 v7, v117, v205
	s_waitcnt vmcnt(25)
	v_fmac_f32_e32 v7, v118, v206
	s_waitcnt vmcnt(24)
	v_fmac_f32_e32 v7, v119, v207
	s_waitcnt vmcnt(23)
	v_fmac_f32_e32 v7, v120, v208
	s_waitcnt vmcnt(22)
	v_fmac_f32_e32 v7, v121, v209
	s_waitcnt vmcnt(21)
	v_fmac_f32_e32 v7, v122, v210
	s_waitcnt vmcnt(20)
	v_fmac_f32_e32 v7, v123, v211
	s_waitcnt vmcnt(19)
	v_fmac_f32_e32 v7, v124, v212
	s_waitcnt vmcnt(18)
	v_fmac_f32_e32 v7, v125, v213
	s_waitcnt vmcnt(17)
	v_fmac_f32_e32 v7, v126, v214
	s_waitcnt vmcnt(16)
	v_fmac_f32_e32 v7, v127, v215
	s_waitcnt vmcnt(15)
	v_fmac_f32_e32 v7, v128, v216
	s_waitcnt vmcnt(14)
	v_fmac_f32_e32 v7, v129, v217
	s_waitcnt vmcnt(13)
	v_fmac_f32_e32 v7, v130, v218
	s_waitcnt vmcnt(12)
	v_fmac_f32_e32 v7, v131, v219
	s_waitcnt vmcnt(11)
	v_fmac_f32_e32 v7, v132, v220
	s_waitcnt vmcnt(10)
	v_fmac_f32_e32 v7, v133, v221
	s_waitcnt vmcnt(9)
	v_fmac_f32_e32 v7, v134, v222
	s_waitcnt vmcnt(8)
	v_fmac_f32_e32 v7, v135, v223
	s_waitcnt vmcnt(7)
	v_fmac_f32_e32 v7, v136, v224
	s_waitcnt vmcnt(6)
	v_fmac_f32_e32 v7, v137, v225
	s_waitcnt vmcnt(5)
	v_fmac_f32_e32 v7, v138, v226
	s_waitcnt vmcnt(4)
	v_fmac_f32_e32 v7, v139, v227
	s_waitcnt vmcnt(3)
	v_fmac_f32_e32 v7, v140, v228
	s_waitcnt vmcnt(2)
	v_fmac_f32_e32 v7, v141, v229
	s_waitcnt vmcnt(1)
	v_fmac_f32_e32 v7, v142, v230
	s_waitcnt vmcnt(0)
	v_fmac_f32_e32 v7, v143, v231
	v_mul_f32_e32 v2, v6, v7
	v_and_b32_e32 v3, 0x7fffffff, v2
	v_cmp_nlt_f32_e64 s[6:7], |v2|, s54
	s_and_saveexec_b64 s[8:9], s[6:7]
	s_xor_b64 s[14:15], exec, s[8:9]
	s_cbranch_execz .LBB0_39
	v_lshrrev_b32_e32 v7, 23, v3
	v_add_u32_e32 v7, 0xffffff88, v7
	v_cmp_lt_u32_e32 vcc, 63, v7
	s_nop 1
	v_cndmask_b32_e32 v8, 0, v68, vcc
	v_add_u32_e32 v7, v8, v7
	v_cmp_lt_u32_e64 s[6:7], 31, v7
	s_nop 1
	v_cndmask_b32_e64 v8, 0, v69, s[6:7]
	v_add_u32_e32 v7, v8, v7
	v_cmp_lt_u32_e64 s[8:9], 31, v7
	s_nop 1
	v_cndmask_b32_e64 v8, 0, v69, s[8:9]
	v_add_u32_e32 v7, v8, v7
	v_and_b32_e32 v8, 0x7fffff, v3
	v_or_b32_e32 v44, 0x800000, v8
	v_mad_u64_u32 v[8:9], s[12:13], v44, s55, 0
	v_mov_b32_e32 v18, v9
	v_mad_u64_u32 v[10:11], s[12:13], v44, s56, v[18:19]
	v_mov_b32_e32 v18, v11
	v_mad_u64_u32 v[12:13], s[12:13], v44, s57, v[18:19]
	v_mov_b32_e32 v18, v13
	v_mad_u64_u32 v[14:15], s[12:13], v44, s58, v[18:19]
	v_mov_b32_e32 v18, v15
	v_mad_u64_u32 v[16:17], s[12:13], v44, s59, v[18:19]
	v_mov_b32_e32 v18, v17
	v_mad_u64_u32 v[42:43], s[12:13], v44, s60, v[18:19]
	v_mov_b32_e32 v18, v43
	v_mad_u64_u32 v[76:77], s[12:13], v44, s61, v[18:19]
	v_cndmask_b32_e32 v9, v42, v14, vcc
	v_cndmask_b32_e32 v11, v76, v16, vcc
	v_cndmask_b32_e32 v15, v77, v42, vcc
	v_cndmask_b32_e64 v13, v11, v9, s[6:7]
	v_cndmask_b32_e64 v11, v15, v11, s[6:7]
	v_cndmask_b32_e32 v15, v16, v12, vcc
	v_cndmask_b32_e64 v9, v9, v15, s[6:7]
	v_cndmask_b32_e64 v11, v11, v13, s[8:9]
	v_cndmask_b32_e64 v13, v13, v9, s[8:9]
	v_sub_u32_e32 v16, 32, v7
	v_alignbit_b32 v17, v11, v13, v16
	v_cmp_eq_u32_e64 s[12:13], 0, v7
	v_cndmask_b32_e32 v10, v14, v10, vcc
	v_cndmask_b32_e32 v8, v12, v8, vcc
	v_cndmask_b32_e64 v7, v17, v11, s[12:13]
	v_cndmask_b32_e64 v11, v15, v10, s[6:7]
	v_cndmask_b32_e64 v9, v9, v11, s[8:9]
	v_alignbit_b32 v14, v13, v9, v16
	v_cndmask_b32_e64 v13, v14, v13, s[12:13]
	v_bfe_u32 v17, v7, 29, 1
	v_cndmask_b32_e64 v8, v10, v8, s[6:7]
	v_alignbit_b32 v14, v7, v13, 30
	v_sub_u32_e32 v18, 0, v17
	v_cndmask_b32_e64 v8, v11, v8, s[8:9]
	v_xor_b32_e32 v14, v14, v18
	v_alignbit_b32 v10, v9, v8, v16
	v_cndmask_b32_e64 v9, v10, v9, s[12:13]
	v_ffbh_u32_e32 v11, v14
	v_alignbit_b32 v10, v13, v9, 30
	v_min_u32_e32 v11, 32, v11
	v_alignbit_b32 v8, v9, v8, 30
	v_xor_b32_e32 v10, v10, v18
	v_sub_u32_e32 v12, 31, v11
	v_xor_b32_e32 v8, v8, v18
	v_alignbit_b32 v13, v14, v10, v12
	v_alignbit_b32 v8, v10, v8, v12
	v_alignbit_b32 v9, v13, v8, 9
	v_ffbh_u32_e32 v10, v9
	v_min_u32_e32 v10, 32, v10
	v_lshrrev_b32_e32 v15, 29, v7
	v_not_b32_e32 v12, v10
	v_alignbit_b32 v8, v9, v8, v12
	v_lshlrev_b32_e32 v9, 31, v15
	v_or_b32_e32 v12, 0x33000000, v9
	v_add_lshl_u32 v10, v10, v11, 23
	v_lshrrev_b32_e32 v8, 9, v8
	v_sub_u32_e32 v10, v12, v10
	v_or_b32_e32 v9, 0.5, v9
	v_lshlrev_b32_e32 v11, 23, v11
	v_or_b32_e32 v8, v10, v8
	v_lshrrev_b32_e32 v10, 9, v13
	v_sub_u32_e32 v9, v9, v11
	v_or_b32_e32 v9, v10, v9
	v_mul_f32_e32 v10, 0x3fc90fda, v9
	v_fma_f32 v11, v9, s62, -v10
	v_fmac_f32_e32 v11, 0x33a22168, v9
	v_fmac_f32_e32 v11, 0x3fc90fda, v8
	v_lshrrev_b32_e32 v7, 30, v7
	v_add_f32_e32 v8, v10, v11
	v_add_u32_e32 v7, v17, v7
; DI void hyena_filter_pos(const Params& p, int t, int w, int lane, float* sz, float* sh0, float* sh1) {
;     ...
;   sh1[w * 64 + lane] = sinf(fr * a);
;   __syncthreads();
;   a = p.f_b3[lane];
; #pragma unroll 4
;   for (int i = 0; i < 64; ++i) a += sh1[w * 64 + i] * p.f_w3[i * 64 + lane];
.LBB0_39:
	s_andn2_saveexec_b64 s[6:7], s[14:15]
	v_mul_f32_e64 v7, |v2|, s63
	v_rndne_f32_e32 v9, v7
	v_cvt_i32_f32_e32 v7, v9
	v_fma_f32 v8, v9, s64, |v2|
	v_fmac_f32_e32 v8, 0xb3a22168, v9
	v_fmac_f32_e32 v8, 0xa7c234c4, v9
	s_or_b64 exec, exec, s[6:7]
	v_mul_f32_e32 v9, v8, v8
	v_fmamk_f32 v10, v9, 0xb94c1982, v65
	v_fmaak_f32 v10, v9, v10, 0xbe2aaa9d
	v_mul_f32_e32 v10, v9, v10
	v_fmac_f32_e32 v8, v8, v10
	v_fmamk_f32 v10, v9, 0x37d75334, v66
	v_fmaak_f32 v10, v9, v10, 0x3d2aabf7
	v_fmaak_f32 v10, v9, v10, 0xbf000004
	v_fma_f32 v9, v9, v10, 1.0
	v_and_b32_e32 v10, 1, v7
	v_lshlrev_b32_e32 v7, 30, v7
	v_cmp_eq_u32_e32 vcc, 0, v10
	v_and_b32_e32 v7, 0x80000000, v7
	v_xor_b32_e32 v3, v3, v2
	v_cndmask_b32_e32 v8, v9, v8, vcc
	v_xor_b32_e32 v3, v3, v7
	v_xor_b32_e32 v3, v3, v8
	v_cmp_class_f32_e64 vcc, v2, s67
	s_mov_b32 s6, 0
	s_nop 0
	v_cndmask_b32_e32 v2, v71, v3, vcc
	ds_write_b32 v51, v2 offset:1664
	s_waitcnt lgkmcnt(0)
	s_barrier
	global_load_dword v7, v[32:33], off
	s_mov_b32 s68, 0x1000
	s_mov_b32 s69, 0
	v_lshl_add_u64 v[234:235], v[38:39], 0, s[68:69]
	v_lshl_add_u64 v[236:237], v[234:235], 0, s[68:69]
	v_lshl_add_u64 v[238:239], v[236:237], 0, s[68:69]
	global_load_dword v167, v[38:39], off offset:-512
	global_load_dword v168, v[38:39], off offset:-256
	global_load_dword v169, v[38:39], off
	global_load_dword v170, v[38:39], off offset:256
	global_load_dword v171, v[38:39], off offset:512
	global_load_dword v172, v[38:39], off offset:768
	global_load_dword v173, v[38:39], off offset:1024
	global_load_dword v174, v[38:39], off offset:1280
	global_load_dword v175, v[38:39], off offset:1536
	global_load_dword v176, v[38:39], off offset:1792
	global_load_dword v177, v[38:39], off offset:2048
	global_load_dword v178, v[38:39], off offset:2304
	global_load_dword v179, v[38:39], off offset:2560
	global_load_dword v180, v[38:39], off offset:2816
	global_load_dword v181, v[38:39], off offset:3072
	global_load_dword v182, v[38:39], off offset:3328
	global_load_dword v183, v[234:235], off offset:-512
	global_load_dword v184, v[234:235], off offset:-256
	global_load_dword v185, v[234:235], off
	global_load_dword v186, v[234:235], off offset:256
	global_load_dword v187, v[234:235], off offset:512
	global_load_dword v188, v[234:235], off offset:768
	global_load_dword v189, v[234:235], off offset:1024
	global_load_dword v190, v[234:235], off offset:1280
	global_load_dword v191, v[234:235], off offset:1536
	global_load_dword v192, v[234:235], off offset:1792
	global_load_dword v193, v[234:235], off offset:2048
	global_load_dword v194, v[234:235], off offset:2304
	global_load_dword v195, v[234:235], off offset:2560
	global_load_dword v197, v[234:235], off offset:2816
	global_load_dword v198, v[234:235], off offset:3072
	global_load_dword v199, v[234:235], off offset:3328
	global_load_dword v200, v[236:237], off offset:-512
	global_load_dword v201, v[236:237], off offset:-256
	global_load_dword v202, v[236:237], off
	global_load_dword v203, v[236:237], off offset:256
	global_load_dword v204, v[236:237], off offset:512
	global_load_dword v205, v[236:237], off offset:768
	global_load_dword v206, v[236:237], off offset:1024
	global_load_dword v207, v[236:237], off offset:1280
	global_load_dword v208, v[236:237], off offset:1536
	global_load_dword v209, v[236:237], off offset:1792
	global_load_dword v210, v[236:237], off offset:2048
	global_load_dword v211, v[236:237], off offset:2304
	global_load_dword v212, v[236:237], off offset:2560
	global_load_dword v213, v[236:237], off offset:2816
	global_load_dword v214, v[236:237], off offset:3072
	global_load_dword v215, v[236:237], off offset:3328
	global_load_dword v216, v[238:239], off offset:-512
	global_load_dword v217, v[238:239], off offset:-256
	global_load_dword v218, v[238:239], off
	global_load_dword v219, v[238:239], off offset:256
	global_load_dword v220, v[238:239], off offset:512
	global_load_dword v221, v[238:239], off offset:768
	global_load_dword v222, v[238:239], off offset:1024
	global_load_dword v223, v[238:239], off offset:1280
	global_load_dword v224, v[238:239], off offset:1536
	global_load_dword v225, v[238:239], off offset:1792
	global_load_dword v226, v[238:239], off offset:2048
	global_load_dword v227, v[238:239], off offset:2304
	global_load_dword v228, v[238:239], off offset:2560
	global_load_dword v229, v[238:239], off offset:2816
	global_load_dword v230, v[238:239], off offset:3072
	global_load_dword v231, v[238:239], off offset:3328
	ds_read_b128 v[80:83], v55
	ds_read_b128 v[84:87], v55 offset:16
	ds_read_b128 v[88:91], v55 offset:32
	ds_read_b128 v[92:95], v55 offset:48
	ds_read_b128 v[96:99], v55 offset:64
	ds_read_b128 v[100:103], v55 offset:80
	ds_read_b128 v[104:107], v55 offset:96
	ds_read_b128 v[108:111], v55 offset:112
	ds_read_b128 v[112:115], v55 offset:128
	ds_read_b128 v[116:119], v55 offset:144
	ds_read_b128 v[120:123], v55 offset:160
	ds_read_b128 v[124:127], v55 offset:176
	ds_read_b128 v[128:131], v55 offset:192
	ds_read_b128 v[132:135], v55 offset:208
	ds_read_b128 v[136:139], v55 offset:224
	ds_read_b128 v[140:143], v55 offset:240
	s_waitcnt lgkmcnt(0)
	s_waitcnt vmcnt(63)
	v_fmac_f32_e32 v7, v80, v167
	s_waitcnt vmcnt(62)
	v_fmac_f32_e32 v7, v81, v168
	s_waitcnt vmcnt(61)
	v_fmac_f32_e32 v7, v82, v169
	s_waitcnt vmcnt(60)
	v_fmac_f32_e32 v7, v83, v170
	s_waitcnt vmcnt(59)
	v_fmac_f32_e32 v7, v84, v171
	s_waitcnt vmcnt(58)
	v_fmac_f32_e32 v7, v85, v172
	s_waitcnt vmcnt(57)
	v_fmac_f32_e32 v7, v86, v173
	s_waitcnt vmcnt(56)
	v_fmac_f32_e32 v7, v87, v174
	s_waitcnt vmcnt(55)
	v_fmac_f32_e32 v7, v88, v175
	s_waitcnt vmcnt(54)
; DI void hyena_filter_pos(const Params& p, int t, int w, int lane, float* sz, float* sh0, float* sh1) {
;     ...
;   for (int i = 0; i < 64; ++i) a += sh1[w * 64 + i] * p.f_w3[i * 64 + lane];
;   __syncthreads();
;   sh0[w * 64 + lane] = sinf(fr * a);
	v_fmac_f32_e32 v7, v89, v176
	s_waitcnt vmcnt(53)
	v_fmac_f32_e32 v7, v90, v177
	s_waitcnt vmcnt(52)
	v_fmac_f32_e32 v7, v91, v178
	s_waitcnt vmcnt(51)
	v_fmac_f32_e32 v7, v92, v179
	s_waitcnt vmcnt(50)
	v_fmac_f32_e32 v7, v93, v180
	s_waitcnt vmcnt(49)
	v_fmac_f32_e32 v7, v94, v181
	s_waitcnt vmcnt(48)
	v_fmac_f32_e32 v7, v95, v182
	s_waitcnt vmcnt(47)
	v_fmac_f32_e32 v7, v96, v183
	s_waitcnt vmcnt(46)
	v_fmac_f32_e32 v7, v97, v184
	s_waitcnt vmcnt(45)
	v_fmac_f32_e32 v7, v98, v185
	s_waitcnt vmcnt(44)
	v_fmac_f32_e32 v7, v99, v186
	s_waitcnt vmcnt(43)
	v_fmac_f32_e32 v7, v100, v187
	s_waitcnt vmcnt(42)
	v_fmac_f32_e32 v7, v101, v188
	s_waitcnt vmcnt(41)
	v_fmac_f32_e32 v7, v102, v189
	s_waitcnt vmcnt(40)
	v_fmac_f32_e32 v7, v103, v190
	s_waitcnt vmcnt(39)
	v_fmac_f32_e32 v7, v104, v191
	s_waitcnt vmcnt(38)
	v_fmac_f32_e32 v7, v105, v192
	s_waitcnt vmcnt(37)
	v_fmac_f32_e32 v7, v106, v193
	s_waitcnt vmcnt(36)
	v_fmac_f32_e32 v7, v107, v194
	s_waitcnt vmcnt(35)
	v_fmac_f32_e32 v7, v108, v195
	s_waitcnt vmcnt(34)
	v_fmac_f32_e32 v7, v109, v197
	s_waitcnt vmcnt(33)
	v_fmac_f32_e32 v7, v110, v198
	s_waitcnt vmcnt(32)
	v_fmac_f32_e32 v7, v111, v199
	s_waitcnt vmcnt(31)
	v_fmac_f32_e32 v7, v112, v200
	s_waitcnt vmcnt(30)
	v_fmac_f32_e32 v7, v113, v201
	s_waitcnt vmcnt(29)
	v_fmac_f32_e32 v7, v114, v202
	s_waitcnt vmcnt(28)
	v_fmac_f32_e32 v7, v115, v203
	s_waitcnt vmcnt(27)
	v_fmac_f32_e32 v7, v116, v204
	s_waitcnt vmcnt(26)
	v_fmac_f32_e32 v7, v117, v205
	s_waitcnt vmcnt(25)
	v_fmac_f32_e32 v7, v118, v206
	s_waitcnt vmcnt(24)
	v_fmac_f32_e32 v7, v119, v207
	s_waitcnt vmcnt(23)
	v_fmac_f32_e32 v7, v120, v208
	s_waitcnt vmcnt(22)
	v_fmac_f32_e32 v7, v121, v209
	s_waitcnt vmcnt(21)
	v_fmac_f32_e32 v7, v122, v210
	s_waitcnt vmcnt(20)
	v_fmac_f32_e32 v7, v123, v211
	s_waitcnt vmcnt(19)
	v_fmac_f32_e32 v7, v124, v212
	s_waitcnt vmcnt(18)
	v_fmac_f32_e32 v7, v125, v213
	s_waitcnt vmcnt(17)
	v_fmac_f32_e32 v7, v126, v214
	s_waitcnt vmcnt(16)
	v_fmac_f32_e32 v7, v127, v215
	s_waitcnt vmcnt(15)
	v_fmac_f32_e32 v7, v128, v216
	s_waitcnt vmcnt(14)
	v_fmac_f32_e32 v7, v129, v217
	s_waitcnt vmcnt(13)
	v_fmac_f32_e32 v7, v130, v218
	s_waitcnt vmcnt(12)
	v_fmac_f32_e32 v7, v131, v219
	s_waitcnt vmcnt(11)
	v_fmac_f32_e32 v7, v132, v220
	s_waitcnt vmcnt(10)
	v_fmac_f32_e32 v7, v133, v221
	s_waitcnt vmcnt(9)
	v_fmac_f32_e32 v7, v134, v222
	s_waitcnt vmcnt(8)
	v_fmac_f32_e32 v7, v135, v223
	s_waitcnt vmcnt(7)
	v_fmac_f32_e32 v7, v136, v224
	s_waitcnt vmcnt(6)
	v_fmac_f32_e32 v7, v137, v225
	s_waitcnt vmcnt(5)
	v_fmac_f32_e32 v7, v138, v226
	s_waitcnt vmcnt(4)
	v_fmac_f32_e32 v7, v139, v227
	s_waitcnt vmcnt(3)
	v_fmac_f32_e32 v7, v140, v228
	s_waitcnt vmcnt(2)
	v_fmac_f32_e32 v7, v141, v229
	s_waitcnt vmcnt(1)
	v_fmac_f32_e32 v7, v142, v230
	s_waitcnt vmcnt(0)
	v_fmac_f32_e32 v7, v143, v231
	v_mul_f32_e32 v2, v6, v7
	v_and_b32_e32 v3, 0x7fffffff, v2
	v_cmp_nlt_f32_e64 s[6:7], |v2|, s54
	s_barrier
	s_and_saveexec_b64 s[8:9], s[6:7]
	s_xor_b64 s[14:15], exec, s[8:9]
	s_cbranch_execz .LBB0_45
	v_lshrrev_b32_e32 v6, 23, v3
	v_add_u32_e32 v6, 0xffffff88, v6
	v_cmp_lt_u32_e32 vcc, 63, v6
	s_nop 1
	v_cndmask_b32_e32 v7, 0, v68, vcc
	v_add_u32_e32 v6, v7, v6
	v_cmp_lt_u32_e64 s[6:7], 31, v6
	s_nop 1
	v_cndmask_b32_e64 v7, 0, v69, s[6:7]
	v_add_u32_e32 v6, v7, v6
	v_cmp_lt_u32_e64 s[8:9], 31, v6
	s_nop 1
	v_cndmask_b32_e64 v7, 0, v69, s[8:9]
	v_add_u32_e32 v44, v7, v6
	v_and_b32_e32 v6, 0x7fffff, v3
	v_or_b32_e32 v42, 0x800000, v6
	v_mad_u64_u32 v[6:7], s[12:13], v42, s55, 0
	v_mov_b32_e32 v18, v7
	v_mad_u64_u32 v[8:9], s[12:13], v42, s56, v[18:19]
	v_mov_b32_e32 v18, v9
	v_mad_u64_u32 v[10:11], s[12:13], v42, s57, v[18:19]
	v_mov_b32_e32 v18, v11
	v_mad_u64_u32 v[12:13], s[12:13], v42, s58, v[18:19]
	v_mov_b32_e32 v18, v13
	v_mad_u64_u32 v[14:15], s[12:13], v42, s59, v[18:19]
	v_mov_b32_e32 v18, v15
	v_mad_u64_u32 v[16:17], s[12:13], v42, s60, v[18:19]
	v_mov_b32_e32 v18, v17
	v_mad_u64_u32 v[42:43], s[12:13], v42, s61, v[18:19]
	v_cndmask_b32_e32 v7, v16, v12, vcc
	v_cndmask_b32_e32 v9, v42, v14, vcc
	v_cndmask_b32_e32 v13, v43, v16, vcc
	v_cndmask_b32_e64 v11, v9, v7, s[6:7]
	v_cndmask_b32_e64 v9, v13, v9, s[6:7]
	v_cndmask_b32_e32 v13, v14, v10, vcc
	v_cndmask_b32_e64 v7, v7, v13, s[6:7]
	v_cndmask_b32_e32 v8, v12, v8, vcc
	v_cndmask_b32_e64 v9, v9, v11, s[8:9]
	v_cndmask_b32_e64 v11, v11, v7, s[8:9]
	v_sub_u32_e32 v14, 32, v44
	v_cndmask_b32_e64 v12, v13, v8, s[6:7]
	v_alignbit_b32 v15, v9, v11, v14
	v_cmp_eq_u32_e64 s[12:13], 0, v44
	v_cndmask_b32_e64 v7, v7, v12, s[8:9]
	v_alignbit_b32 v13, v11, v7, v14
	v_cndmask_b32_e64 v9, v15, v9, s[12:13]
	v_cndmask_b32_e32 v6, v10, v6, vcc
	v_cndmask_b32_e64 v11, v13, v11, s[12:13]
	v_bfe_u32 v16, v9, 29, 1
	v_cndmask_b32_e64 v6, v8, v6, s[6:7]
	v_alignbit_b32 v13, v9, v11, 30
	v_sub_u32_e32 v17, 0, v16
	v_cndmask_b32_e64 v6, v12, v6, s[8:9]
	v_xor_b32_e32 v13, v13, v17
	v_alignbit_b32 v8, v7, v6, v14
	v_cndmask_b32_e64 v7, v8, v7, s[12:13]
	v_ffbh_u32_e32 v10, v13
	v_alignbit_b32 v8, v11, v7, 30
	v_min_u32_e32 v10, 32, v10
	v_alignbit_b32 v6, v7, v6, 30
	v_xor_b32_e32 v8, v8, v17
	v_sub_u32_e32 v11, 31, v10
	v_xor_b32_e32 v6, v6, v17
	v_alignbit_b32 v12, v13, v8, v11
	v_alignbit_b32 v6, v8, v6, v11
	v_alignbit_b32 v7, v12, v6, 9
	v_ffbh_u32_e32 v8, v7
	v_min_u32_e32 v8, 32, v8
	v_lshrrev_b32_e32 v15, 29, v9
	v_not_b32_e32 v11, v8
	v_alignbit_b32 v6, v7, v6, v11
	v_lshlrev_b32_e32 v7, 31, v15
	v_or_b32_e32 v11, 0x33000000, v7
	v_add_lshl_u32 v8, v8, v10, 23
	v_lshrrev_b32_e32 v6, 9, v6
	v_sub_u32_e32 v8, v11, v8
	v_or_b32_e32 v7, 0.5, v7
	v_lshlrev_b32_e32 v10, 23, v10
	v_or_b32_e32 v6, v8, v6
	v_lshrrev_b32_e32 v8, 9, v12
	v_sub_u32_e32 v7, v7, v10
	v_or_b32_e32 v7, v8, v7
	v_mul_f32_e32 v8, 0x3fc90fda, v7
	v_fma_f32 v10, v7, s62, -v8
	v_fmac_f32_e32 v10, 0x33a22168, v7
	v_fmac_f32_e32 v10, 0x3fc90fda, v6
	v_lshrrev_b32_e32 v6, 30, v9
	v_add_f32_e32 v7, v8, v10
	v_add_u32_e32 v6, v16, v6
; DI void hyena_filter_pos(const Params& p, int t, int w, int lane, float* sz, float* sh0, float* sh1) {
;     ...
;   sh0[w * 64 + lane] = sinf(fr * a);
;   __syncthreads();
;   bf16_t* filt = (bf16_t*)(p.ws + OFF_FILT);
;   const float dmin = logf(1e-2f) / 1.5f, dmax = logf(1e-2f) / 0.3f;
; #pragma unroll 1
;   for (int i = 0; i < 16; ++i) {
;     int n = lane + 64 * i;
;     float o = 0.f;
; #pragma unroll 4
;     for (int k = 0; k < 64; ++k) o += sh0[w * 64 + k] * p.f_w4[k * 1024 + n];
.LBB0_45:
	s_andn2_saveexec_b64 s[6:7], s[14:15]
	v_mul_f32_e64 v6, |v2|, s63
	v_rndne_f32_e32 v8, v6
	v_cvt_i32_f32_e32 v6, v8
	v_fma_f32 v7, v8, s64, |v2|
	v_fmac_f32_e32 v7, 0xb3a22168, v8
	v_fmac_f32_e32 v7, 0xa7c234c4, v8
	s_or_b64 exec, exec, s[6:7]
	v_mul_f32_e32 v8, v7, v7
	v_fmamk_f32 v9, v8, 0xb94c1982, v65
	v_fmaak_f32 v9, v8, v9, 0xbe2aaa9d
	v_mul_f32_e32 v9, v8, v9
	v_fmac_f32_e32 v7, v7, v9
	v_fmamk_f32 v9, v8, 0x37d75334, v66
	v_fmaak_f32 v9, v8, v9, 0x3d2aabf7
	v_fmaak_f32 v9, v8, v9, 0xbf000004
	v_fma_f32 v8, v8, v9, 1.0
	v_and_b32_e32 v9, 1, v6
	v_lshlrev_b32_e32 v6, 30, v6
	v_cmp_eq_u32_e32 vcc, 0, v9
	v_and_b32_e32 v6, 0x80000000, v6
	v_xor_b32_e32 v3, v3, v2
	v_cndmask_b32_e32 v7, v8, v7, vcc
	v_xor_b32_e32 v3, v3, v6
	v_xor_b32_e32 v3, v3, v7
	v_cmp_class_f32_e64 vcc, v2, s67
	s_mov_b32 s14, 0
	v_cmp_eq_u32_e64 s[6:7], 0, v4
	v_cndmask_b32_e32 v2, v71, v3, vcc
	ds_write_b32 v51, v2 offset:640
	v_cmp_ne_u32_e64 s[8:9], 0, v4
	v_mov_b64_e32 v[2:3], v[40:41]
	s_waitcnt lgkmcnt(0)
	s_barrier
	v_readlane_b32 s70, v40, 0
	v_readlane_b32 s71, v41, 0
	s_nop 1
	s_add_u32 s72, s70, 0x10000
	s_addc_u32 s73, s71, 0
	s_add_u32 s74, s72, 0x10000
	s_addc_u32 s75, s73, 0
	s_add_u32 s76, s74, 0x10000
	s_addc_u32 s77, s75, 0
	v_subrev_u32_e32 v151, s70, v40
	v_add_u32_e32 v152, 0x1000, v151
	v_add_u32_e32 v153, 0x2000, v151
	v_add_u32_e32 v154, 0x3000, v151
	v_add_u32_e32 v155, 0x4000, v151
	v_add_u32_e32 v156, 0x5000, v151
	v_add_u32_e32 v157, 0x6000, v151
	v_add_u32_e32 v158, 0x7000, v151
	v_add_u32_e32 v159, 0x8000, v151
	v_add_u32_e32 v160, 0x9000, v151
	v_add_u32_e32 v161, 0xa000, v151
	v_add_u32_e32 v162, 0xb000, v151
	v_add_u32_e32 v163, 0xc000, v151
	v_add_u32_e32 v164, 0xd000, v151
	v_add_u32_e32 v165, 0xe000, v151
	v_add_u32_e32 v166, 0xf000, v151
	ds_read_b128 v[80:83], v54
	ds_read_b128 v[84:87], v54 offset:16
	ds_read_b128 v[88:91], v54 offset:32
	ds_read_b128 v[92:95], v54 offset:48
	ds_read_b128 v[96:99], v54 offset:64
	ds_read_b128 v[100:103], v54 offset:80
	ds_read_b128 v[104:107], v54 offset:96
	ds_read_b128 v[108:111], v54 offset:112
	ds_read_b128 v[112:115], v54 offset:128
	ds_read_b128 v[116:119], v54 offset:144
	ds_read_b128 v[120:123], v54 offset:160
	ds_read_b128 v[124:127], v54 offset:176
	ds_read_b128 v[128:131], v54 offset:192
	ds_read_b128 v[132:135], v54 offset:208
	ds_read_b128 v[136:139], v54 offset:224
	ds_read_b128 v[140:143], v54 offset:240
	global_load_dword v167, v151, s[70:71]
	global_load_dword v168, v152, s[70:71]
	global_load_dword v169, v153, s[70:71]
	global_load_dword v170, v154, s[70:71]
	global_load_dword v171, v155, s[70:71]
	global_load_dword v172, v156, s[70:71]
	global_load_dword v173, v157, s[70:71]
	global_load_dword v174, v158, s[70:71]
	global_load_dword v175, v159, s[70:71]
	global_load_dword v176, v160, s[70:71]
	global_load_dword v177, v161, s[70:71]
	global_load_dword v178, v162, s[70:71]
	global_load_dword v179, v163, s[70:71]
	global_load_dword v180, v164, s[70:71]
	global_load_dword v181, v165, s[70:71]
	global_load_dword v182, v166, s[70:71]
	global_load_dword v183, v151, s[72:73]
	global_load_dword v184, v152, s[72:73]
	global_load_dword v185, v153, s[72:73]
	global_load_dword v186, v154, s[72:73]
	global_load_dword v187, v155, s[72:73]
	global_load_dword v188, v156, s[72:73]
	global_load_dword v189, v157, s[72:73]
	global_load_dword v190, v158, s[72:73]
	global_load_dword v191, v159, s[72:73]
	global_load_dword v192, v160, s[72:73]
	global_load_dword v193, v161, s[72:73]
	global_load_dword v194, v162, s[72:73]
	global_load_dword v195, v163, s[72:73]
	global_load_dword v197, v164, s[72:73]
	global_load_dword v198, v165, s[72:73]
	global_load_dword v199, v166, s[72:73]
	global_load_dword v200, v151, s[74:75]
	global_load_dword v201, v152, s[74:75]
	global_load_dword v202, v153, s[74:75]
	global_load_dword v203, v154, s[74:75]
	global_load_dword v204, v155, s[74:75]
	global_load_dword v205, v156, s[74:75]
	global_load_dword v206, v157, s[74:75]
	global_load_dword v207, v158, s[74:75]
	global_load_dword v208, v159, s[74:75]
	global_load_dword v209, v160, s[74:75]
	global_load_dword v210, v161, s[74:75]
	global_load_dword v211, v162, s[74:75]
	global_load_dword v212, v163, s[74:75]
	global_load_dword v213, v164, s[74:75]
	global_load_dword v214, v165, s[74:75]
	global_load_dword v215, v166, s[74:75]
	global_load_dword v216, v151, s[76:77]
	global_load_dword v217, v152, s[76:77]
	global_load_dword v218, v153, s[76:77]
	global_load_dword v219, v154, s[76:77]
	global_load_dword v220, v155, s[76:77]
	global_load_dword v221, v156, s[76:77]
	global_load_dword v222, v157, s[76:77]
	global_load_dword v223, v158, s[76:77]
	global_load_dword v224, v159, s[76:77]
	global_load_dword v225, v160, s[76:77]
	global_load_dword v226, v161, s[76:77]
	global_load_dword v227, v162, s[76:77]
	global_load_dword v228, v163, s[76:77]
	global_load_dword v229, v164, s[76:77]
	global_load_dword v230, v165, s[76:77]
	global_load_dword v231, v166, s[76:77]
	s_waitcnt lgkmcnt(0)
	s_branch .LBB0_50

; DI void hyena_filter_pos(const Params& p, int t, int w, int lane, float* sz, float* sh0, float* sh1) {
;     ...
;   for (int i = 0; i < 16; ++i) {
;     int n = lane + 64 * i;
;     float o = 0.f;
; #pragma unroll 4
;     for (int k = 0; k < 64; ++k) o += sh0[w * 64 + k] * p.f_w4[k * 1024 + n];
.LBB0_50:
	v_mov_b32_e32 v6, 0
	s_cmp_eq_u32 s14, 15
	s_cbranch_scc1 .Lfilt_last
	s_waitcnt vmcnt(63)
	v_fmac_f32_e32 v6, v80, v167
	global_load_dword v167, v151, s[70:71] offset:256
	s_waitcnt vmcnt(63)
	v_fmac_f32_e32 v6, v81, v168
	global_load_dword v168, v152, s[70:71] offset:256
	s_waitcnt vmcnt(63)
	v_fmac_f32_e32 v6, v82, v169
	global_load_dword v169, v153, s[70:71] offset:256
	s_waitcnt vmcnt(63)
	v_fmac_f32_e32 v6, v83, v170
	global_load_dword v170, v154, s[70:71] offset:256
	s_waitcnt vmcnt(63)
	v_fmac_f32_e32 v6, v84, v171
	global_load_dword v171, v155, s[70:71] offset:256
	s_waitcnt vmcnt(63)
	v_fmac_f32_e32 v6, v85, v172
	global_load_dword v172, v156, s[70:71] offset:256
	s_waitcnt vmcnt(63)
	v_fmac_f32_e32 v6, v86, v173
	global_load_dword v173, v157, s[70:71] offset:256
	s_waitcnt vmcnt(63)
	v_fmac_f32_e32 v6, v87, v174
	global_load_dword v174, v158, s[70:71] offset:256
	s_waitcnt vmcnt(63)
	v_fmac_f32_e32 v6, v88, v175
	global_load_dword v175, v159, s[70:71] offset:256
	s_waitcnt vmcnt(63)
	v_fmac_f32_e32 v6, v89, v176
	global_load_dword v176, v160, s[70:71] offset:256
	s_waitcnt vmcnt(63)
	v_fmac_f32_e32 v6, v90, v177
	global_load_dword v177, v161, s[70:71] offset:256
	s_waitcnt vmcnt(63)
	v_fmac_f32_e32 v6, v91, v178
	global_load_dword v178, v162, s[70:71] offset:256
	s_waitcnt vmcnt(63)
	v_fmac_f32_e32 v6, v92, v179
	global_load_dword v179, v163, s[70:71] offset:256
	s_waitcnt vmcnt(63)
	v_fmac_f32_e32 v6, v93, v180
	global_load_dword v180, v164, s[70:71] offset:256
	s_waitcnt vmcnt(63)
	v_fmac_f32_e32 v6, v94, v181
	global_load_dword v181, v165, s[70:71] offset:256
	s_waitcnt vmcnt(63)
	v_fmac_f32_e32 v6, v95, v182
	global_load_dword v182, v166, s[70:71] offset:256
	s_waitcnt vmcnt(63)
	v_fmac_f32_e32 v6, v96, v183
	global_load_dword v183, v151, s[72:73] offset:256
	s_waitcnt vmcnt(63)
	v_fmac_f32_e32 v6, v97, v184
	global_load_dword v184, v152, s[72:73] offset:256
	s_waitcnt vmcnt(63)
	v_fmac_f32_e32 v6, v98, v185
	global_load_dword v185, v153, s[72:73] offset:256
	s_waitcnt vmcnt(63)
	v_fmac_f32_e32 v6, v99, v186
	global_load_dword v186, v154, s[72:73] offset:256
	s_waitcnt vmcnt(63)
	v_fmac_f32_e32 v6, v100, v187
	global_load_dword v187, v155, s[72:73] offset:256
	s_waitcnt vmcnt(63)
	v_fmac_f32_e32 v6, v101, v188
	global_load_dword v188, v156, s[72:73] offset:256
	s_waitcnt vmcnt(63)
	v_fmac_f32_e32 v6, v102, v189
	global_load_dword v189, v157, s[72:73] offset:256
	s_waitcnt vmcnt(63)
	v_fmac_f32_e32 v6, v103, v190
	global_load_dword v190, v158, s[72:73] offset:256
	s_waitcnt vmcnt(63)
	v_fmac_f32_e32 v6, v104, v191
	global_load_dword v191, v159, s[72:73] offset:256
	s_waitcnt vmcnt(63)
	v_fmac_f32_e32 v6, v105, v192
	global_load_dword v192, v160, s[72:73] offset:256
	s_waitcnt vmcnt(63)
	v_fmac_f32_e32 v6, v106, v193
	global_load_dword v193, v161, s[72:73] offset:256
	s_waitcnt vmcnt(63)
	v_fmac_f32_e32 v6, v107, v194
	global_load_dword v194, v162, s[72:73] offset:256
	s_waitcnt vmcnt(63)
	v_fmac_f32_e32 v6, v108, v195
	global_load_dword v195, v163, s[72:73] offset:256
	s_waitcnt vmcnt(63)
	v_fmac_f32_e32 v6, v109, v197
	global_load_dword v197, v164, s[72:73] offset:256
	s_waitcnt vmcnt(63)
	v_fmac_f32_e32 v6, v110, v198
	global_load_dword v198, v165, s[72:73] offset:256
	s_waitcnt vmcnt(63)
	v_fmac_f32_e32 v6, v111, v199
	global_load_dword v199, v166, s[72:73] offset:256
	s_waitcnt vmcnt(63)
	v_fmac_f32_e32 v6, v112, v200
	global_load_dword v200, v151, s[74:75] offset:256
	s_waitcnt vmcnt(63)
	v_fmac_f32_e32 v6, v113, v201
	global_load_dword v201, v152, s[74:75] offset:256
	s_waitcnt vmcnt(63)
	v_fmac_f32_e32 v6, v114, v202
	global_load_dword v202, v153, s[74:75] offset:256
	s_waitcnt vmcnt(63)
	v_fmac_f32_e32 v6, v115, v203
	global_load_dword v203, v154, s[74:75] offset:256
	s_waitcnt vmcnt(63)
	v_fmac_f32_e32 v6, v116, v204
	global_load_dword v204, v155, s[74:75] offset:256
	s_waitcnt vmcnt(63)
	v_fmac_f32_e32 v6, v117, v205
	global_load_dword v205, v156, s[74:75] offset:256
	s_waitcnt vmcnt(63)
	v_fmac_f32_e32 v6, v118, v206
	global_load_dword v206, v157, s[74:75] offset:256
	s_waitcnt vmcnt(63)
	v_fmac_f32_e32 v6, v119, v207
	global_load_dword v207, v158, s[74:75] offset:256
	s_waitcnt vmcnt(63)
	v_fmac_f32_e32 v6, v120, v208
	global_load_dword v208, v159, s[74:75] offset:256
	s_waitcnt vmcnt(63)
	v_fmac_f32_e32 v6, v121, v209
	global_load_dword v209, v160, s[74:75] offset:256
	s_waitcnt vmcnt(63)
	v_fmac_f32_e32 v6, v122, v210
	global_load_dword v210, v161, s[74:75] offset:256
	s_waitcnt vmcnt(63)
	v_fmac_f32_e32 v6, v123, v211
	global_load_dword v211, v162, s[74:75] offset:256
	s_waitcnt vmcnt(63)
	v_fmac_f32_e32 v6, v124, v212
	global_load_dword v212, v163, s[74:75] offset:256
	s_waitcnt vmcnt(63)
	v_fmac_f32_e32 v6, v125, v213
	global_load_dword v213, v164, s[74:75] offset:256
	s_waitcnt vmcnt(63)
	v_fmac_f32_e32 v6, v126, v214
	global_load_dword v214, v165, s[74:75] offset:256
	s_waitcnt vmcnt(63)
	v_fmac_f32_e32 v6, v127, v215
	global_load_dword v215, v166, s[74:75] offset:256
	s_waitcnt vmcnt(63)
	v_fmac_f32_e32 v6, v128, v216
	global_load_dword v216, v151, s[76:77] offset:256
	s_waitcnt vmcnt(63)
	v_fmac_f32_e32 v6, v129, v217
	global_load_dword v217, v152, s[76:77] offset:256
	s_waitcnt vmcnt(63)
	v_fmac_f32_e32 v6, v130, v218
	global_load_dword v218, v153, s[76:77] offset:256
	s_waitcnt vmcnt(63)
	v_fmac_f32_e32 v6, v131, v219
	global_load_dword v219, v154, s[76:77] offset:256
	s_waitcnt vmcnt(63)
	v_fmac_f32_e32 v6, v132, v220
	global_load_dword v220, v155, s[76:77] offset:256
	s_waitcnt vmcnt(63)
	v_fmac_f32_e32 v6, v133, v221
	global_load_dword v221, v156, s[76:77] offset:256
	s_waitcnt vmcnt(63)
	v_fmac_f32_e32 v6, v134, v222
	global_load_dword v222, v157, s[76:77] offset:256
	s_waitcnt vmcnt(63)
	v_fmac_f32_e32 v6, v135, v223
	global_load_dword v223, v158, s[76:77] offset:256
	s_waitcnt vmcnt(63)
	v_fmac_f32_e32 v6, v136, v224
	global_load_dword v224, v159, s[76:77] offset:256
	s_waitcnt vmcnt(63)
	v_fmac_f32_e32 v6, v137, v225
	global_load_dword v225, v160, s[76:77] offset:256
	s_waitcnt vmcnt(63)
	v_fmac_f32_e32 v6, v138, v226
	global_load_dword v226, v161, s[76:77] offset:256
	s_waitcnt vmcnt(63)
	v_fmac_f32_e32 v6, v139, v227
	global_load_dword v227, v162, s[76:77] offset:256
	s_waitcnt vmcnt(63)
	v_fmac_f32_e32 v6, v140, v228
	global_load_dword v228, v163, s[76:77] offset:256
	s_waitcnt vmcnt(63)
	v_fmac_f32_e32 v6, v141, v229
	global_load_dword v229, v164, s[76:77] offset:256
	s_waitcnt vmcnt(63)
	v_fmac_f32_e32 v6, v142, v230
	global_load_dword v230, v165, s[76:77] offset:256
	s_waitcnt vmcnt(63)
	v_fmac_f32_e32 v6, v143, v231
	global_load_dword v231, v166, s[76:77] offset:256
	s_add_u32 s70, s70, 0x100
	s_addc_u32 s71, s71, 0
	s_add_u32 s72, s72, 0x100
	s_addc_u32 s73, s73, 0
	s_add_u32 s74, s74, 0x100
	s_addc_u32 s75, s75, 0
	s_add_u32 s76, s76, 0x100
	s_addc_u32 s77, s77, 0
	s_branch .Lfilt_epi
; DI bf16_t f2bf(float x) { return (bf16_t)(pack2(x, 0.f) & 0xffffu); }
; DI void hyena_filter_pos(const Params& p, int t, int w, int lane, float* sz, float* sh0, float* sh1) {
;     ...
;     for (int k = 0; k < 64; ++k) o += sh0[w * 64 + k] * p.f_w4[k * 1024 + n];
;     int c = n & 511;
;     float delta = dmin + (float)c * ((dmax - dmin) / 511.f);
;     float win = expf(-tn * fabsf(delta));
;     o *= win;
;     if (n < 512) {
;       if (t == 0) o += p.hy_bias[c];
;       filt[(size_t)c * 8192 + 4096 + t] = f2bf(o);
;     } else {
;       if (t == 0) filt[(size_t)c * 8192] = 0;
;       else filt[(size_t)c * 8192 + 4096 - t] = f2bf(o);
.Lfilt_last:
	s_waitcnt vmcnt(63)
	v_fmac_f32_e32 v6, v80, v167
	s_waitcnt vmcnt(62)
	v_fmac_f32_e32 v6, v81, v168
	s_waitcnt vmcnt(61)
	v_fmac_f32_e32 v6, v82, v169
	s_waitcnt vmcnt(60)
	v_fmac_f32_e32 v6, v83, v170
	s_waitcnt vmcnt(59)
	v_fmac_f32_e32 v6, v84, v171
	s_waitcnt vmcnt(58)
	v_fmac_f32_e32 v6, v85, v172
	s_waitcnt vmcnt(57)
	v_fmac_f32_e32 v6, v86, v173
	s_waitcnt vmcnt(56)
	v_fmac_f32_e32 v6, v87, v174
	s_waitcnt vmcnt(55)
	v_fmac_f32_e32 v6, v88, v175
	s_waitcnt vmcnt(54)
	v_fmac_f32_e32 v6, v89, v176
	s_waitcnt vmcnt(53)
	v_fmac_f32_e32 v6, v90, v177
	s_waitcnt vmcnt(52)
	v_fmac_f32_e32 v6, v91, v178
	s_waitcnt vmcnt(51)
	v_fmac_f32_e32 v6, v92, v179
	s_waitcnt vmcnt(50)
	v_fmac_f32_e32 v6, v93, v180
	s_waitcnt vmcnt(49)
	v_fmac_f32_e32 v6, v94, v181
	s_waitcnt vmcnt(48)
	v_fmac_f32_e32 v6, v95, v182
	s_waitcnt vmcnt(47)
	v_fmac_f32_e32 v6, v96, v183
	s_waitcnt vmcnt(46)
	v_fmac_f32_e32 v6, v97, v184
	s_waitcnt vmcnt(45)
	v_fmac_f32_e32 v6, v98, v185
	s_waitcnt vmcnt(44)
	v_fmac_f32_e32 v6, v99, v186
	s_waitcnt vmcnt(43)
	v_fmac_f32_e32 v6, v100, v187
	s_waitcnt vmcnt(42)
	v_fmac_f32_e32 v6, v101, v188
	s_waitcnt vmcnt(41)
	v_fmac_f32_e32 v6, v102, v189
	s_waitcnt vmcnt(40)
	v_fmac_f32_e32 v6, v103, v190
	s_waitcnt vmcnt(39)
	v_fmac_f32_e32 v6, v104, v191
	s_waitcnt vmcnt(38)
	v_fmac_f32_e32 v6, v105, v192
	s_waitcnt vmcnt(37)
	v_fmac_f32_e32 v6, v106, v193
	s_waitcnt vmcnt(36)
	v_fmac_f32_e32 v6, v107, v194
	s_waitcnt vmcnt(35)
	v_fmac_f32_e32 v6, v108, v195
	s_waitcnt vmcnt(34)
	v_fmac_f32_e32 v6, v109, v197
	s_waitcnt vmcnt(33)
	v_fmac_f32_e32 v6, v110, v198
	s_waitcnt vmcnt(32)
	v_fmac_f32_e32 v6, v111, v199
	s_waitcnt vmcnt(31)
	v_fmac_f32_e32 v6, v112, v200
	s_waitcnt vmcnt(30)
	v_fmac_f32_e32 v6, v113, v201
	s_waitcnt vmcnt(29)
	v_fmac_f32_e32 v6, v114, v202
	s_waitcnt vmcnt(28)
	v_fmac_f32_e32 v6, v115, v203
	s_waitcnt vmcnt(27)
	v_fmac_f32_e32 v6, v116, v204
	s_waitcnt vmcnt(26)
	v_fmac_f32_e32 v6, v117, v205
	s_waitcnt vmcnt(25)
	v_fmac_f32_e32 v6, v118, v206
	s_waitcnt vmcnt(24)
	v_fmac_f32_e32 v6, v119, v207
	s_waitcnt vmcnt(23)
	v_fmac_f32_e32 v6, v120, v208
	s_waitcnt vmcnt(22)
	v_fmac_f32_e32 v6, v121, v209
	s_waitcnt vmcnt(21)
	v_fmac_f32_e32 v6, v122, v210
	s_waitcnt vmcnt(20)
	v_fmac_f32_e32 v6, v123, v211
	s_waitcnt vmcnt(19)
	v_fmac_f32_e32 v6, v124, v212
	s_waitcnt vmcnt(18)
	v_fmac_f32_e32 v6, v125, v213
	s_waitcnt vmcnt(17)
	v_fmac_f32_e32 v6, v126, v214
	s_waitcnt vmcnt(16)
	v_fmac_f32_e32 v6, v127, v215
	s_waitcnt vmcnt(15)
	v_fmac_f32_e32 v6, v128, v216
	s_waitcnt vmcnt(14)
	v_fmac_f32_e32 v6, v129, v217
	s_waitcnt vmcnt(13)
	v_fmac_f32_e32 v6, v130, v218
	s_waitcnt vmcnt(12)
	v_fmac_f32_e32 v6, v131, v219
	s_waitcnt vmcnt(11)
	v_fmac_f32_e32 v6, v132, v220
	s_waitcnt vmcnt(10)
	v_fmac_f32_e32 v6, v133, v221
	s_waitcnt vmcnt(9)
	v_fmac_f32_e32 v6, v134, v222
	s_waitcnt vmcnt(8)
	v_fmac_f32_e32 v6, v135, v223
	s_waitcnt vmcnt(7)
	v_fmac_f32_e32 v6, v136, v224
	s_waitcnt vmcnt(6)
	v_fmac_f32_e32 v6, v137, v225
	s_waitcnt vmcnt(5)
	v_fmac_f32_e32 v6, v138, v226
	s_waitcnt vmcnt(4)
	v_fmac_f32_e32 v6, v139, v227
	s_waitcnt vmcnt(3)
	v_fmac_f32_e32 v6, v140, v228
	s_waitcnt vmcnt(2)
	v_fmac_f32_e32 v6, v141, v229
	s_waitcnt vmcnt(1)
	v_fmac_f32_e32 v6, v142, v230
	s_waitcnt vmcnt(0)
	v_fmac_f32_e32 v6, v143, v231
.Lfilt_epi:
	s_lshl_b32 s15, s14, 6
	v_bitop3_b32 v7, s15, v72, v1 bitop3:0xc8
	v_cvt_f32_u32_e32 v8, v7
	s_mov_b32 s12, 0x3fb8aa3b
	s_cmp_gt_u32 s14, 7
	v_fmamk_f32 v8, v8, 0xbcc4df2d, v67
	v_mul_f32_e64 v8, |v8|, -v5
	v_mul_f32_e32 v9, 0x3fb8aa3b, v8
	v_fma_f32 v10, v8, s12, -v9
	v_rndne_f32_e32 v11, v9
	v_fmac_f32_e32 v10, 0x32a5705f, v8
	v_sub_f32_e32 v9, v9, v11
	v_add_f32_e32 v9, v9, v10
	v_cvt_i32_f32_e32 v11, v11
	v_exp_f32_e32 v9, v9
	s_mov_b32 s12, 0xc2ce8ed0
	v_cmp_ngt_f32_e32 vcc, s12, v8
	s_mov_b32 s12, 0x42b17218
	v_ldexp_f32 v9, v9, v11
	v_cndmask_b32_e32 v9, 0, v9, vcc
	v_cmp_nlt_f32_e32 vcc, s12, v8
	s_mov_b64 s[12:13], -1
	s_nop 0
	v_cndmask_b32_e32 v8, v73, v9, vcc
	v_mul_f32_e32 v6, v8, v6
	s_cbranch_scc0 .LBB0_58
	s_and_saveexec_b64 s[12:13], s[8:9]
	s_xor_b64 s[12:13], exec, s[12:13]
	s_cbranch_execz .LBB0_55
	v_lshlrev_b32_e32 v8, 13, v7
	v_sub_u32_e32 v8, v8, v4
	v_ashrrev_i32_e32 v9, 31, v8
	v_lshl_add_u64 v[8:9], v[8:9], 1, s[18:19]
	v_add_co_u32_e32 v8, vcc, 0x2000, v8
	v_cvt_pk_bf16_f32 v10, v6, s0
	s_nop 0
	v_addc_co_u32_e32 v9, vcc, 0, v9, vcc
	global_store_short v[8:9], v10, off
